# compress unit stage 2: the 16 k-steps' strided w2 loads issued as two 56-load batches (+bias) instead of 16 serialized load->wait->MFMA round trips
# speedup vs baseline: 1.0034x; 1.0014x over previous
.Lcp_noload1:
	ds_read_b128 v[100:103], v165 offset:8192
	ds_read_b128 v[132:135], v167
	ds_read_b128 v[104:107], v165 offset:9216
	ds_read_b128 v[136:139], v167 offset:32
	ds_read_b128 v[108:111], v165 offset:10240
	ds_read_b128 v[140:143], v167 offset:64
	ds_read_b128 v[112:115], v165 offset:11264
	ds_read_b128 v[144:147], v167 offset:96
	ds_read_b128 v[116:119], v165 offset:12288
	ds_read_b128 v[148:151], v167 offset:128
	ds_read_b128 v[120:123], v165 offset:13312
	ds_read_b128 v[152:155], v167 offset:160
	ds_read_b128 v[124:127], v165 offset:14336
	ds_read_b128 v[156:159], v167 offset:192
	s_waitcnt lgkmcnt(12)
	v_mfma_f32_32x32x16_bf16 v[2:17], v[100:103], v[132:135], v[2:17]
	ds_read_b128 v[128:131], v165 offset:15360
	ds_read_b128 v[160:163], v167 offset:224
	s_waitcnt lgkmcnt(12)
	v_mfma_f32_32x32x16_bf16 v[2:17], v[104:107], v[136:139], v[2:17]
	s_waitcnt lgkmcnt(10)
	v_mfma_f32_32x32x16_bf16 v[2:17], v[108:111], v[140:143], v[2:17]
	s_waitcnt lgkmcnt(8)
	v_mfma_f32_32x32x16_bf16 v[2:17], v[112:115], v[144:147], v[2:17]
	s_waitcnt lgkmcnt(6)
	v_mfma_f32_32x32x16_bf16 v[2:17], v[116:119], v[148:151], v[2:17]
	s_waitcnt lgkmcnt(4)
	v_mfma_f32_32x32x16_bf16 v[2:17], v[120:123], v[152:155], v[2:17]
	s_waitcnt lgkmcnt(2)
	v_mfma_f32_32x32x16_bf16 v[2:17], v[124:127], v[156:159], v[2:17]
	s_waitcnt lgkmcnt(0)
	v_mfma_f32_32x32x16_bf16 v[2:17], v[128:131], v[160:163], v[2:17]
	s_sub_i32 vcc_lo, vcc_lo, 1
	s_cmp_lg_u32 vcc_lo, 0
	s_cbranch_scc1 .Lcp_loop
	s_lshl_b32 s6, s94, 8
	s_mov_b32 s7, s95
	s_lshl_b64 s[6:7], s[6:7], 2
	s_add_u32 s6, s18, s6
	s_addc_u32 s7, s19, s7
	v_lshl_add_u64 v[18:19], v[26:27], 2, s[6:7]
	global_load_dword v0, v[18:19], off
	v_lshl_add_u32 v18, v26, 1, 0
	s_movk_i32 s6, 0x840
	v_lshl_or_b32 v30, v36, 2, 1
	v_cmp_gt_i32_e32 vcc, 2, v39
	s_waitcnt vmcnt(0)
	v_add_f32_e32 v2, v2, v0
	v_mul_f32_e32 v19, 0x3d372713, v2
	v_mul_f32_e32 v19, v2, v19
	v_fma_f32 v19, v2, v19, v2
	v_mul_f32_e32 v19, 0x3f4c422a, v19
	v_mul_f32_e32 v19, 0xc038aa3b, v19
	v_exp_f32_e32 v19, v19
	s_nop 0
	v_add_f32_e32 v19, 1.0, v19
	v_rcp_f32_e32 v19, v19
	s_nop 0
	v_mul_f32_e32 v2, v2, v19
	v_cvt_pk_bf16_f32 v2, v2, s0
	v_mad_u32_u24 v19, v36, s6, v18
	ds_write_b16 v19, v2
	v_add_f32_e32 v2, v3, v0
	v_mul_f32_e32 v3, 0x3d372713, v2
	v_mul_f32_e32 v3, v2, v3
	v_fma_f32 v3, v2, v3, v2
	v_mul_f32_e32 v3, 0x3f4c422a, v3
	v_mul_f32_e32 v3, 0xc038aa3b, v3
	v_exp_f32_e32 v3, v3
	s_movk_i32 s6, 0x210
	v_add_f32_e32 v3, 1.0, v3
	v_rcp_f32_e32 v3, v3
	s_nop 0
	v_mul_f32_e32 v2, v2, v3
	v_cvt_pk_bf16_f32 v3, v2, s0
	v_mad_u32_u24 v2, v30, s6, v18
	ds_write_b16 v2, v3
	v_add_f32_e32 v3, v4, v0
	v_mul_f32_e32 v4, 0x3d372713, v3
	v_mul_f32_e32 v4, v3, v4
	v_fma_f32 v4, v3, v4, v3
	v_mul_f32_e32 v4, 0x3f4c422a, v4
	v_mul_f32_e32 v4, 0xc038aa3b, v4
	v_exp_f32_e32 v4, v4
	s_nop 0
	v_add_f32_e32 v4, 1.0, v4
	v_rcp_f32_e32 v4, v4
	s_nop 0
	v_mul_f32_e32 v3, v3, v4
	v_cvt_pk_bf16_f32 v3, v3, s0
	ds_write_b16 v2, v3 offset:528
	v_add_f32_e32 v3, v5, v0
	v_mul_f32_e32 v4, 0x3d372713, v3
	v_mul_f32_e32 v4, v3, v4
	v_fma_f32 v4, v3, v4, v3
	v_mul_f32_e32 v4, 0x3f4c422a, v4
	v_mul_f32_e32 v4, 0xc038aa3b, v4
	v_exp_f32_e32 v4, v4
	s_nop 0
	v_add_f32_e32 v4, 1.0, v4
	v_rcp_f32_e32 v4, v4
	s_nop 0
	v_mul_f32_e32 v3, v3, v4
	v_cvt_pk_bf16_f32 v3, v3, s0
	ds_write_b16 v2, v3 offset:1056
	v_add_f32_e32 v3, v6, v0
	v_mul_f32_e32 v4, 0x3d372713, v3
	v_mul_f32_e32 v4, v3, v4
	v_fma_f32 v4, v3, v4, v3
	v_mul_f32_e32 v4, 0x3f4c422a, v4
	v_mul_f32_e32 v4, 0xc038aa3b, v4
	v_exp_f32_e32 v4, v4
	s_nop 0
	v_add_f32_e32 v4, 1.0, v4
	v_rcp_f32_e32 v4, v4
	s_nop 0
	v_mul_f32_e32 v3, v3, v4
	v_cvt_pk_bf16_f32 v3, v3, s0
	ds_write_b16 v2, v3 offset:3696
	v_add_f32_e32 v3, v7, v0
	v_mul_f32_e32 v4, 0x3d372713, v3
	v_mul_f32_e32 v4, v3, v4
	v_fma_f32 v4, v3, v4, v3
	v_mul_f32_e32 v4, 0x3f4c422a, v4
	v_mul_f32_e32 v4, 0xc038aa3b, v4
	v_exp_f32_e32 v4, v4
	s_nop 0
	v_add_f32_e32 v4, 1.0, v4
	v_rcp_f32_e32 v4, v4
	s_nop 0
	v_mul_f32_e32 v3, v3, v4
	v_cvt_pk_bf16_f32 v3, v3, s0
	ds_write_b16 v2, v3 offset:4224
	v_add_f32_e32 v3, v8, v0
	v_mul_f32_e32 v4, 0x3d372713, v3
	v_mul_f32_e32 v4, v3, v4
	v_fma_f32 v4, v3, v4, v3
	v_mul_f32_e32 v4, 0x3f4c422a, v4
	v_mul_f32_e32 v4, 0xc038aa3b, v4
	v_exp_f32_e32 v4, v4
	s_nop 0
	v_add_f32_e32 v4, 1.0, v4
	v_rcp_f32_e32 v4, v4
	s_nop 0
	v_mul_f32_e32 v3, v3, v4
	v_cvt_pk_bf16_f32 v3, v3, s0
	ds_write_b16 v2, v3 offset:4752
	v_add_f32_e32 v3, v9, v0
	v_mul_f32_e32 v4, 0x3d372713, v3
	v_mul_f32_e32 v4, v3, v4
	v_fma_f32 v4, v3, v4, v3
	v_mul_f32_e32 v4, 0x3f4c422a, v4
	v_mul_f32_e32 v4, 0xc038aa3b, v4
	v_exp_f32_e32 v4, v4
	s_nop 0
	v_add_f32_e32 v4, 1.0, v4
	v_rcp_f32_e32 v4, v4
	s_nop 0
	v_mul_f32_e32 v3, v3, v4
	v_cvt_pk_bf16_f32 v3, v3, s0
	ds_write_b16 v2, v3 offset:5280
	v_add_f32_e32 v3, v10, v0
	v_mul_f32_e32 v4, 0x3d372713, v3
	v_mul_f32_e32 v4, v3, v4
	v_fma_f32 v4, v3, v4, v3
	v_mul_f32_e32 v4, 0x3f4c422a, v4
	v_mul_f32_e32 v4, 0xc038aa3b, v4
	v_exp_f32_e32 v4, v4
	s_nop 0
	v_add_f32_e32 v4, 1.0, v4
	v_rcp_f32_e32 v4, v4
	s_nop 0
	v_mul_f32_e32 v3, v3, v4
	v_cvt_pk_bf16_f32 v3, v3, s0
	ds_write_b16 v2, v3 offset:7920
	v_add_f32_e32 v3, v11, v0
	v_mul_f32_e32 v4, 0x3d372713, v3
	v_mul_f32_e32 v4, v3, v4
	v_fma_f32 v4, v3, v4, v3
	v_mul_f32_e32 v4, 0x3f4c422a, v4
	v_mul_f32_e32 v4, 0xc038aa3b, v4
	v_exp_f32_e32 v4, v4
	s_nop 0
	v_add_f32_e32 v4, 1.0, v4
	v_rcp_f32_e32 v4, v4
	s_nop 0
	v_mul_f32_e32 v3, v3, v4
	v_cvt_pk_bf16_f32 v3, v3, s0
	ds_write_b16 v2, v3 offset:8448
	v_add_f32_e32 v3, v12, v0
	v_mul_f32_e32 v4, 0x3d372713, v3
	v_mul_f32_e32 v4, v3, v4
	v_fma_f32 v4, v3, v4, v3
	v_mul_f32_e32 v4, 0x3f4c422a, v4
	v_mul_f32_e32 v4, 0xc038aa3b, v4
	v_exp_f32_e32 v4, v4
	s_nop 0
	v_add_f32_e32 v4, 1.0, v4
	v_rcp_f32_e32 v4, v4
	s_nop 0
	v_mul_f32_e32 v3, v3, v4
	v_cvt_pk_bf16_f32 v3, v3, s0
	ds_write_b16 v2, v3 offset:8976
	v_add_f32_e32 v3, v13, v0
	v_mul_f32_e32 v4, 0x3d372713, v3
	v_mul_f32_e32 v4, v3, v4
	v_fma_f32 v4, v3, v4, v3
	v_mul_f32_e32 v4, 0x3f4c422a, v4
	v_mul_f32_e32 v4, 0xc038aa3b, v4
	v_exp_f32_e32 v4, v4
	s_nop 0
	v_add_f32_e32 v4, 1.0, v4
	v_rcp_f32_e32 v4, v4
	s_nop 0
	v_mul_f32_e32 v3, v3, v4
	v_cvt_pk_bf16_f32 v3, v3, s0
	ds_write_b16 v2, v3 offset:9504
	v_add_f32_e32 v3, v14, v0
	v_mul_f32_e32 v4, 0x3d372713, v3
	v_mul_f32_e32 v4, v3, v4
	v_fma_f32 v4, v3, v4, v3
	v_mul_f32_e32 v4, 0x3f4c422a, v4
	v_mul_f32_e32 v4, 0xc038aa3b, v4
	v_exp_f32_e32 v4, v4
	s_nop 0
	v_add_f32_e32 v4, 1.0, v4
	v_rcp_f32_e32 v4, v4
	s_nop 0
	v_mul_f32_e32 v3, v3, v4
	v_cvt_pk_bf16_f32 v3, v3, s0
	ds_write_b16 v2, v3 offset:12144
	v_add_f32_e32 v3, v15, v0
	v_mul_f32_e32 v4, 0x3d372713, v3
	v_mul_f32_e32 v4, v3, v4
	v_fma_f32 v4, v3, v4, v3
	v_mul_f32_e32 v4, 0x3f4c422a, v4
	v_mul_f32_e32 v4, 0xc038aa3b, v4
	v_exp_f32_e32 v4, v4
	s_nop 0
	v_add_f32_e32 v4, 1.0, v4
	v_rcp_f32_e32 v4, v4
	s_nop 0
	v_mul_f32_e32 v3, v3, v4
	v_cvt_pk_bf16_f32 v3, v3, s0
	ds_write_b16 v2, v3 offset:12672
	v_add_f32_e32 v3, v16, v0
	v_mul_f32_e32 v4, 0x3d372713, v3
	v_mul_f32_e32 v4, v3, v4
	v_fma_f32 v4, v3, v4, v3
	v_mul_f32_e32 v4, 0x3f4c422a, v4
	v_mul_f32_e32 v4, 0xc038aa3b, v4
	v_exp_f32_e32 v4, v4
	v_add_f32_e32 v0, v17, v0
	v_add_f32_e32 v4, 1.0, v4
	v_rcp_f32_e32 v4, v4
	s_nop 0
	v_mul_f32_e32 v3, v3, v4
	v_cvt_pk_bf16_f32 v3, v3, s0
	ds_write_b16 v2, v3 offset:13200
	v_mul_f32_e32 v3, 0x3d372713, v0
	v_mul_f32_e32 v3, v0, v3
	v_fma_f32 v3, v0, v3, v0
	v_mul_f32_e32 v3, 0x3f4c422a, v3
	v_mul_f32_e32 v3, 0xc038aa3b, v3
	v_exp_f32_e32 v3, v3
	s_nop 0
	v_add_f32_e32 v3, 1.0, v3
	v_rcp_f32_e32 v3, v3
	s_nop 0
	v_mul_f32_e32 v0, v0, v3
	v_cvt_pk_bf16_f32 v0, v0, s0
	ds_write_b16 v2, v0 offset:13728
	s_waitcnt lgkmcnt(0)
	s_barrier
	s_and_saveexec_b64 s[6:7], vcc
	s_mov_b32 s28, 0x40c00000
	s_cbranch_execz .LBB0_1783
	s_lshl_b64 s[18:19], s[94:95], 16
	s_add_u32 s18, s8, s18
	s_addc_u32 s19, s9, s19
	s_lshl_b32 s94, s94, 6
	s_lshl_b64 s[8:9], s[94:95], 2
	s_add_u32 s8, s16, s8
	s_movk_i32 s16, 0x210
	v_mad_u32_u24 v31, v38, s16, 0
	v_lshlrev_b64 v[22:23], 2, v[26:27]
	v_lshl_add_u32 v0, v36, 4, v31
	v_lshl_add_u64 v[24:25], s[18:19], 0, v[22:23]
	ds_read_b128 v[2:5], v0
	v_lshlrev_b32_e32 v0, 11, v36
	v_lshl_add_u64 v[28:29], v[24:25], 0, v[0:1]
	s_mov_b32 s100, 0x2000
	s_mov_b32 s101, 0
	v_lshl_add_u64 v[164:165], v[28:29], 0, s[100:101]
	global_load_dword v52, v[164:165], off
	global_load_dword v53, v[164:165], off offset:256
	global_load_dword v54, v[164:165], off offset:512
	global_load_dword v55, v[164:165], off offset:768
	global_load_dword v56, v[164:165], off offset:1024
	global_load_dword v57, v[164:165], off offset:1280
	global_load_dword v58, v[164:165], off offset:1536
	global_load_dword v59, v[164:165], off offset:1792
	s_mov_b32 s100, 0x3000
	s_mov_b32 s101, 0
	v_lshl_add_u64 v[164:165], v[28:29], 0, s[100:101]
	global_load_dword v60, v[164:165], off
	global_load_dword v61, v[164:165], off offset:256
	global_load_dword v62, v[164:165], off offset:512
	global_load_dword v63, v[164:165], off offset:768
	global_load_dword v64, v[164:165], off offset:1024
	global_load_dword v65, v[164:165], off offset:1280
	global_load_dword v66, v[164:165], off offset:1536
	global_load_dword v67, v[164:165], off offset:1792
	s_mov_b32 s100, 0x4000
	s_mov_b32 s101, 0
	v_lshl_add_u64 v[164:165], v[28:29], 0, s[100:101]
	global_load_dword v68, v[164:165], off
	global_load_dword v69, v[164:165], off offset:256
	global_load_dword v70, v[164:165], off offset:512
	global_load_dword v71, v[164:165], off offset:768
	global_load_dword v72, v[164:165], off offset:1024
	global_load_dword v73, v[164:165], off offset:1280
	global_load_dword v74, v[164:165], off offset:1536
	global_load_dword v75, v[164:165], off offset:1792
	s_mov_b32 s100, 0x5000
	s_mov_b32 s101, 0
	v_lshl_add_u64 v[164:165], v[28:29], 0, s[100:101]
	global_load_dword v76, v[164:165], off
	global_load_dword v77, v[164:165], off offset:256
	global_load_dword v78, v[164:165], off offset:512
	global_load_dword v79, v[164:165], off offset:768
	global_load_dword v80, v[164:165], off offset:1024
	global_load_dword v81, v[164:165], off offset:1280
	global_load_dword v82, v[164:165], off offset:1536
	global_load_dword v83, v[164:165], off offset:1792
	s_mov_b32 s100, 0x6000
	s_mov_b32 s101, 0
	v_lshl_add_u64 v[164:165], v[28:29], 0, s[100:101]
	global_load_dword v84, v[164:165], off
	global_load_dword v85, v[164:165], off offset:256
	global_load_dword v86, v[164:165], off offset:512
	global_load_dword v87, v[164:165], off offset:768
	global_load_dword v88, v[164:165], off offset:1024
	global_load_dword v89, v[164:165], off offset:1280
	global_load_dword v90, v[164:165], off offset:1536
	global_load_dword v91, v[164:165], off offset:1792
	s_mov_b32 s100, 0x7000
	s_mov_b32 s101, 0
	v_lshl_add_u64 v[164:165], v[28:29], 0, s[100:101]
	global_load_dword v92, v[164:165], off
	global_load_dword v93, v[164:165], off offset:256
	global_load_dword v94, v[164:165], off offset:512
	global_load_dword v95, v[164:165], off offset:768
	global_load_dword v96, v[164:165], off offset:1024
	global_load_dword v97, v[164:165], off offset:1280
	global_load_dword v98, v[164:165], off offset:1536
	global_load_dword v99, v[164:165], off offset:1792
	s_mov_b32 s100, 0x8000
	s_mov_b32 s101, 0
	v_lshl_add_u64 v[164:165], v[28:29], 0, s[100:101]
	global_load_dword v100, v[164:165], off
	global_load_dword v101, v[164:165], off offset:256
	global_load_dword v102, v[164:165], off offset:512
	global_load_dword v103, v[164:165], off offset:768
	global_load_dword v104, v[164:165], off offset:1024
	global_load_dword v105, v[164:165], off offset:1280
	global_load_dword v106, v[164:165], off offset:1536
	global_load_dword v107, v[164:165], off offset:1792
	global_load_dword v0, v[28:29], off
	global_load_dword v6, v[28:29], off offset:256
	global_load_dword v7, v[28:29], off offset:512
	global_load_dword v8, v[28:29], off offset:768
	global_load_dword v9, v[28:29], off offset:1024
	global_load_dword v10, v[28:29], off offset:1280
	global_load_dword v11, v[28:29], off offset:1536
	global_load_dword v12, v[28:29], off offset:1792
	s_movk_i32 s16, 0x1000
	s_addc_u32 s9, s17, s9
	s_waitcnt vmcnt(6)
	v_cvt_pk_bf16_f32 v6, v0, v6
	v_or_b32_e32 v0, 16, v37
	v_lshl_add_u32 v18, v0, 1, v31
	v_lshlrev_b32_e32 v0, 8, v0
	v_lshl_add_u64 v[32:33], v[24:25], 0, v[0:1]
	global_load_dword v0, v[32:33], off
	v_add_co_u32_e32 v32, vcc, s16, v28
	ds_read_b128 v[18:21], v18
	s_nop 0
	v_addc_co_u32_e32 v33, vcc, 0, v29, vcc
	global_load_dword v27, v[32:33], off offset:256
	global_load_dword v39, v[32:33], off offset:512
	global_load_dword v40, v[32:33], off offset:768
	global_load_dword v41, v[32:33], off offset:1024
	global_load_dword v42, v[32:33], off offset:1280
	global_load_dword v43, v[32:33], off offset:1536
	s_nop 0
	global_load_dword v32, v[32:33], off offset:1792
	s_waitcnt vmcnt(12)
	v_cvt_pk_bf16_f32 v7, v7, v8
	s_waitcnt vmcnt(10)
	v_cvt_pk_bf16_f32 v8, v9, v10
	s_waitcnt vmcnt(8)
	v_cvt_pk_bf16_f32 v9, v11, v12
	s_movk_i32 s16, 0x3000
	s_waitcnt vmcnt(6)
	v_cvt_pk_bf16_f32 v38, v0, v27
	s_waitcnt lgkmcnt(1)
	v_mfma_f32_32x32x16_bf16 v[2:17], v[2:5], v[6:9], 0
	s_waitcnt vmcnt(4)
	v_cvt_pk_bf16_f32 v39, v39, v40
	v_or_b32_e32 v0, 32, v37
	s_waitcnt vmcnt(2)
	v_cvt_pk_bf16_f32 v40, v41, v42
	s_waitcnt vmcnt(0)
	v_cvt_pk_bf16_f32 v41, v43, v32
	s_waitcnt lgkmcnt(0)
	s_nop 0
	v_lshl_add_u64 v[164:165], s[8:9], 0, v[22:23]
	global_load_dword v166, v[164:165], off
	s_mov_b32 s100, 0x9000
	s_mov_b32 s101, 0
	v_lshl_add_u64 v[164:165], v[28:29], 0, s[100:101]
	global_load_dword v108, v[164:165], off
	global_load_dword v109, v[164:165], off offset:256
	global_load_dword v110, v[164:165], off offset:512
	global_load_dword v111, v[164:165], off offset:768
	global_load_dword v112, v[164:165], off offset:1024
	global_load_dword v113, v[164:165], off offset:1280
	global_load_dword v114, v[164:165], off offset:1536
	global_load_dword v115, v[164:165], off offset:1792
	s_mov_b32 s100, 0xa000
	s_mov_b32 s101, 0
	v_lshl_add_u64 v[164:165], v[28:29], 0, s[100:101]
	global_load_dword v116, v[164:165], off
	global_load_dword v117, v[164:165], off offset:256
	global_load_dword v118, v[164:165], off offset:512
	global_load_dword v119, v[164:165], off offset:768
	global_load_dword v120, v[164:165], off offset:1024
	global_load_dword v121, v[164:165], off offset:1280
	global_load_dword v122, v[164:165], off offset:1536
	global_load_dword v123, v[164:165], off offset:1792
	s_mov_b32 s100, 0xb000
	s_mov_b32 s101, 0
	v_lshl_add_u64 v[164:165], v[28:29], 0, s[100:101]
	global_load_dword v124, v[164:165], off
	global_load_dword v125, v[164:165], off offset:256
	global_load_dword v126, v[164:165], off offset:512
	global_load_dword v127, v[164:165], off offset:768
	global_load_dword v128, v[164:165], off offset:1024
	global_load_dword v129, v[164:165], off offset:1280
	global_load_dword v130, v[164:165], off offset:1536
	global_load_dword v131, v[164:165], off offset:1792
	s_mov_b32 s100, 0xc000
	s_mov_b32 s101, 0
	v_lshl_add_u64 v[164:165], v[28:29], 0, s[100:101]
	global_load_dword v132, v[164:165], off
	global_load_dword v133, v[164:165], off offset:256
	global_load_dword v134, v[164:165], off offset:512
	global_load_dword v135, v[164:165], off offset:768
	global_load_dword v136, v[164:165], off offset:1024
	global_load_dword v137, v[164:165], off offset:1280
	global_load_dword v138, v[164:165], off offset:1536
	global_load_dword v139, v[164:165], off offset:1792
	s_mov_b32 s100, 0xd000
	s_mov_b32 s101, 0
	v_lshl_add_u64 v[164:165], v[28:29], 0, s[100:101]
	global_load_dword v140, v[164:165], off
	global_load_dword v141, v[164:165], off offset:256
	global_load_dword v142, v[164:165], off offset:512
	global_load_dword v143, v[164:165], off offset:768
	global_load_dword v144, v[164:165], off offset:1024
	global_load_dword v145, v[164:165], off offset:1280
	global_load_dword v146, v[164:165], off offset:1536
	global_load_dword v147, v[164:165], off offset:1792
	s_mov_b32 s100, 0xe000
	s_mov_b32 s101, 0
	v_lshl_add_u64 v[164:165], v[28:29], 0, s[100:101]
	global_load_dword v148, v[164:165], off
	global_load_dword v149, v[164:165], off offset:256
	global_load_dword v150, v[164:165], off offset:512
	global_load_dword v151, v[164:165], off offset:768
	global_load_dword v152, v[164:165], off offset:1024
	global_load_dword v153, v[164:165], off offset:1280
	global_load_dword v154, v[164:165], off offset:1536
	global_load_dword v155, v[164:165], off offset:1792
	s_mov_b32 s100, 0xf000
	s_mov_b32 s101, 0
	v_lshl_add_u64 v[164:165], v[28:29], 0, s[100:101]
	global_load_dword v156, v[164:165], off
	global_load_dword v157, v[164:165], off offset:256
	global_load_dword v158, v[164:165], off offset:512
	global_load_dword v159, v[164:165], off offset:768
	global_load_dword v160, v[164:165], off offset:1024
	global_load_dword v161, v[164:165], off offset:1280
	global_load_dword v162, v[164:165], off offset:1536
	global_load_dword v163, v[164:165], off offset:1792
	v_mfma_f32_32x32x16_bf16 v[2:17], v[18:21], v[38:41], v[2:17]
	v_lshl_add_u32 v18, v0, 1, v31
	v_lshlrev_b32_e32 v0, 8, v0
	ds_read_b128 v[18:21], v18
	s_nop 0
	s_nop 0
	v_cvt_pk_bf16_f32 v38, v52, v53
	v_or_b32_e32 v0, 48, v37
	v_cvt_pk_bf16_f32 v39, v54, v55
	v_cvt_pk_bf16_f32 v40, v56, v57
	v_cvt_pk_bf16_f32 v41, v58, v59
	s_waitcnt lgkmcnt(0)
	s_nop 0
	v_mfma_f32_32x32x16_bf16 v[2:17], v[18:21], v[38:41], v[2:17]
	v_lshl_add_u32 v18, v0, 1, v31
	v_lshlrev_b32_e32 v0, 8, v0
	ds_read_b128 v[18:21], v18
	s_nop 0
	s_nop 0
	s_movk_i32 s16, 0x4000
	v_cvt_pk_bf16_f32 v38, v60, v61
	v_or_b32_e32 v0, 64, v37
	v_cvt_pk_bf16_f32 v39, v62, v63
	v_cvt_pk_bf16_f32 v40, v64, v65
	v_cvt_pk_bf16_f32 v41, v66, v67
	s_waitcnt lgkmcnt(0)
	s_nop 0
	v_mfma_f32_32x32x16_bf16 v[2:17], v[18:21], v[38:41], v[2:17]
	v_lshl_add_u32 v18, v0, 1, v31
	v_lshlrev_b32_e32 v0, 8, v0
	ds_read_b128 v[18:21], v18
	s_nop 0
	s_nop 0
	s_movk_i32 s16, 0x5000
	v_cvt_pk_bf16_f32 v38, v68, v69
	v_or_b32_e32 v0, 0x50, v37
	v_cvt_pk_bf16_f32 v39, v70, v71
	v_cvt_pk_bf16_f32 v40, v72, v73
	v_cvt_pk_bf16_f32 v41, v74, v75
	s_waitcnt lgkmcnt(0)
	s_nop 0
	v_mfma_f32_32x32x16_bf16 v[2:17], v[18:21], v[38:41], v[2:17]
	v_lshl_add_u32 v18, v0, 1, v31
	v_lshlrev_b32_e32 v0, 8, v0
	ds_read_b128 v[18:21], v18
	s_nop 0
	s_nop 0
	s_movk_i32 s16, 0x6000
	v_cvt_pk_bf16_f32 v38, v76, v77
	v_or_b32_e32 v0, 0x60, v37
	v_cvt_pk_bf16_f32 v39, v78, v79
	v_cvt_pk_bf16_f32 v40, v80, v81
	v_cvt_pk_bf16_f32 v41, v82, v83
	s_waitcnt lgkmcnt(0)
	s_nop 0
	v_mfma_f32_32x32x16_bf16 v[2:17], v[18:21], v[38:41], v[2:17]
	v_lshl_add_u32 v18, v0, 1, v31
	v_lshlrev_b32_e32 v0, 8, v0
	ds_read_b128 v[18:21], v18
	s_nop 0
	s_nop 0
	s_movk_i32 s16, 0x7000
	v_cvt_pk_bf16_f32 v38, v84, v85
	v_or_b32_e32 v0, 0x70, v37
	v_cvt_pk_bf16_f32 v39, v86, v87
	v_cvt_pk_bf16_f32 v40, v88, v89
	v_cvt_pk_bf16_f32 v41, v90, v91
	s_waitcnt lgkmcnt(0)
	s_nop 0
	v_mfma_f32_32x32x16_bf16 v[2:17], v[18:21], v[38:41], v[2:17]
	v_lshl_add_u32 v18, v0, 1, v31
	v_lshlrev_b32_e32 v0, 8, v0
	ds_read_b128 v[18:21], v18
	s_nop 0
	s_nop 0
	s_mov_b32 s16, 0x9000
	v_cvt_pk_bf16_f32 v38, v92, v93
	v_or_b32_e32 v0, 0x80, v37
	v_cvt_pk_bf16_f32 v39, v94, v95
	v_cvt_pk_bf16_f32 v40, v96, v97
	v_cvt_pk_bf16_f32 v41, v98, v99
	s_waitcnt lgkmcnt(0)
	s_nop 0
	v_mfma_f32_32x32x16_bf16 v[2:17], v[18:21], v[38:41], v[2:17]
	v_lshl_add_u32 v18, v0, 1, v31
	v_lshlrev_b32_e32 v0, 8, v0
	ds_read_b128 v[18:21], v18
	s_nop 0
	s_nop 0
	v_cvt_pk_bf16_f32 v38, v100, v101
	v_or_b32_e32 v0, 0x90, v37
	v_cvt_pk_bf16_f32 v39, v102, v103
	v_cvt_pk_bf16_f32 v40, v104, v105
	v_cvt_pk_bf16_f32 v41, v106, v107
	s_waitcnt lgkmcnt(0)
	s_nop 0
	v_mfma_f32_32x32x16_bf16 v[2:17], v[18:21], v[38:41], v[2:17]
	v_lshl_add_u32 v18, v0, 1, v31
	v_lshlrev_b32_e32 v0, 8, v0
	ds_read_b128 v[18:21], v18
	s_nop 0
	s_nop 0
	s_mov_b32 s16, 0xa000
	s_waitcnt vmcnt(48)
	v_cvt_pk_bf16_f32 v38, v108, v109
	v_or_b32_e32 v0, 0xa0, v37
	v_cvt_pk_bf16_f32 v39, v110, v111
	v_cvt_pk_bf16_f32 v40, v112, v113
	v_cvt_pk_bf16_f32 v41, v114, v115
	s_waitcnt lgkmcnt(0)
	s_nop 0
	v_mfma_f32_32x32x16_bf16 v[2:17], v[18:21], v[38:41], v[2:17]
	v_lshl_add_u32 v18, v0, 1, v31
	v_lshlrev_b32_e32 v0, 8, v0
	ds_read_b128 v[18:21], v18
	s_nop 0
	s_nop 0
	s_mov_b32 s16, 0xb000
	s_waitcnt vmcnt(40)
	v_cvt_pk_bf16_f32 v38, v116, v117
	v_or_b32_e32 v0, 0xb0, v37
	v_cvt_pk_bf16_f32 v39, v118, v119
	v_cvt_pk_bf16_f32 v40, v120, v121
	v_cvt_pk_bf16_f32 v41, v122, v123
	s_waitcnt lgkmcnt(0)
	s_nop 0
	v_mfma_f32_32x32x16_bf16 v[2:17], v[18:21], v[38:41], v[2:17]
	v_lshl_add_u32 v18, v0, 1, v31
	v_lshlrev_b32_e32 v0, 8, v0
	ds_read_b128 v[18:21], v18
	s_nop 0
	s_nop 0
	s_mov_b32 s16, 0xc000
	s_waitcnt vmcnt(32)
	v_cvt_pk_bf16_f32 v38, v124, v125
	v_or_b32_e32 v0, 0xc0, v37
	v_cvt_pk_bf16_f32 v39, v126, v127
	v_cvt_pk_bf16_f32 v40, v128, v129
	v_cvt_pk_bf16_f32 v41, v130, v131
	s_waitcnt lgkmcnt(0)
	s_nop 0
	v_mfma_f32_32x32x16_bf16 v[2:17], v[18:21], v[38:41], v[2:17]
	v_lshl_add_u32 v18, v0, 1, v31
	v_lshlrev_b32_e32 v0, 8, v0
	ds_read_b128 v[18:21], v18
	s_nop 0
	s_nop 0
	s_mov_b32 s16, 0xd000
	s_waitcnt vmcnt(24)
	v_cvt_pk_bf16_f32 v38, v132, v133
	v_or_b32_e32 v0, 0xd0, v37
	v_cvt_pk_bf16_f32 v39, v134, v135
	v_cvt_pk_bf16_f32 v40, v136, v137
	v_cvt_pk_bf16_f32 v41, v138, v139
	s_waitcnt lgkmcnt(0)
	s_nop 0
	v_mfma_f32_32x32x16_bf16 v[2:17], v[18:21], v[38:41], v[2:17]
	v_lshl_add_u32 v18, v0, 1, v31
	v_lshlrev_b32_e32 v0, 8, v0
	ds_read_b128 v[18:21], v18
	s_nop 0
	s_nop 0
	s_mov_b32 s16, 0xe000
	s_waitcnt vmcnt(16)
	v_cvt_pk_bf16_f32 v38, v140, v141
	v_or_b32_e32 v0, 0xe0, v37
	v_cvt_pk_bf16_f32 v39, v142, v143
	v_cvt_pk_bf16_f32 v40, v144, v145
	v_cvt_pk_bf16_f32 v41, v146, v147
	s_waitcnt lgkmcnt(0)
	s_nop 0
	v_mfma_f32_32x32x16_bf16 v[2:17], v[18:21], v[38:41], v[2:17]
	v_lshl_add_u32 v18, v0, 1, v31
	v_lshlrev_b32_e32 v0, 8, v0
	ds_read_b128 v[18:21], v18
	s_nop 0
	s_nop 0
	s_mov_b32 s16, 0xf000
	s_waitcnt vmcnt(8)
	v_cvt_pk_bf16_f32 v38, v148, v149
	v_or_b32_e32 v0, 0xf0, v37
	v_cvt_pk_bf16_f32 v39, v150, v151
	v_cvt_pk_bf16_f32 v40, v152, v153
	v_cvt_pk_bf16_f32 v41, v154, v155
	s_waitcnt lgkmcnt(0)
	s_nop 0
	v_mfma_f32_32x32x16_bf16 v[2:17], v[18:21], v[38:41], v[2:17]
	v_lshl_add_u32 v18, v0, 1, v31
	v_lshlrev_b32_e32 v0, 8, v0
	ds_read_b128 v[18:21], v18
	s_nop 0
	s_nop 0
	s_waitcnt vmcnt(0)
	v_cvt_pk_bf16_f32 v38, v156, v157
	v_cvt_pk_bf16_f32 v39, v158, v159
	v_cvt_pk_bf16_f32 v40, v160, v161
	v_cvt_pk_bf16_f32 v41, v162, v163
	s_waitcnt lgkmcnt(0)
	s_nop 0
	v_mfma_f32_32x32x16_bf16 v[2:17], v[18:21], v[38:41], v[2:17]
	v_lshl_add_u64 v[18:19], s[8:9], 0, v[22:23]
	v_mov_b32_e32 v0, v166
	v_lshl_add_u32 v18, v26, 2, 0
	s_movk_i32 s8, 0x410
	v_mad_u32_u24 v19, v36, s8, v18
	s_movk_i32 s8, 0x104
	s_waitcnt vmcnt(0)
	s_nop 4
	v_add_f32_e32 v2, v0, v2
	ds_write_b32 v19, v2 offset:18432
	v_add_f32_e32 v2, v0, v3
	v_mad_u32_u24 v3, v30, s8, v18
	v_add_f32_e32 v4, v0, v4
	v_add_u32_e32 v18, 0x4800, v3
	ds_write2_b32 v18, v2, v4 offset1:65
	v_add_f32_e32 v2, v0, v5
	ds_write_b32 v3, v2 offset:18952
	v_add_f32_e32 v2, v0, v6
	v_add_f32_e32 v4, v0, v7
	v_add_u32_e32 v5, 0x4e00, v3
	ds_write2_b32 v5, v2, v4 offset0:71 offset1:136
	v_add_f32_e32 v2, v0, v8
	v_add_f32_e32 v4, v0, v9
	v_add_u32_e32 v5, 0x5000, v3
	ds_write2_b32 v5, v2, v4 offset0:73 offset1:138
	v_add_f32_e32 v2, v0, v10
	v_add_f32_e32 v4, v0, v11
	v_add_u32_e32 v5, 0x5600, v3
	ds_write2_b32 v5, v2, v4 offset0:79 offset1:144
	v_add_f32_e32 v2, v0, v12
	v_add_f32_e32 v4, v0, v13
	v_add_u32_e32 v5, 0x5800, v3
	ds_write2_b32 v5, v2, v4 offset0:81 offset1:146
	v_add_f32_e32 v2, v0, v14
	v_add_f32_e32 v4, v0, v15
	v_add_u32_e32 v5, 0x5e00, v3
	ds_write2_b32 v5, v2, v4 offset0:87 offset1:152
	v_add_f32_e32 v2, v0, v16
	v_add_f32_e32 v0, v0, v17
	v_add_u32_e32 v3, 0x6000, v3
	ds_write2_b32 v3, v2, v0 offset0:89 offset1:154
